# GEMM unit start (P5,P7,P8,P10): compiler's preheader vmcnt(0) flush removed, K-loop counted waits only (v29 + unitwait)
# baseline (speedup 1.0000x reference)
.LBB0_588:
	s_ashr_i32 s35, s34, 31
	s_lshl_b64 s[36:37], s[34:35], 20
	s_add_u32 s36, s60, s36
	s_addc_u32 s37, s61, s37
	s_and_b64 s[38:39], s[8:9], exec
	s_cselect_b32 s35, s37, s49
	s_cselect_b32 s41, s36, s48
	s_ashr_i32 s31, s30, 31
	s_lshl_b64 s[38:39], s[30:31], 20
	s_add_u32 s38, s62, s38
	s_addc_u32 s39, s63, s39
	s_and_b64 s[54:55], s[8:9], exec
	s_cselect_b32 s31, s39, s51
	s_cselect_b32 s73, s38, s50
	s_add_u32 s48, s48, 0x80080
	s_addc_u32 s49, s49, 0
	s_add_u32 s74, s50, 0x100
	v_mov_b32_e32 v0, 0
	s_addc_u32 s75, s51, 0
	s_mov_b32 s77, -2
	s_waitcnt lgkmcnt(0)
	v_mov_b32_e32 v1, v0
	v_mov_b32_e32 v2, v0
	v_mov_b32_e32 v3, v0
	v_mov_b32_e32 v4, v0
	v_mov_b32_e32 v5, v0
	v_mov_b32_e32 v6, v0
	v_mov_b32_e32 v7, v0
	v_mov_b32_e32 v16, v0
	v_mov_b32_e32 v17, v0
	v_mov_b32_e32 v18, v0
	v_mov_b32_e32 v19, v0
	v_mov_b32_e32 v20, v0
	v_mov_b32_e32 v21, v0
	v_mov_b32_e32 v22, v0
	v_mov_b32_e32 v23, v0
	v_mov_b32_e32 v32, v0
	v_mov_b32_e32 v33, v0
	v_mov_b32_e32 v34, v0
	v_mov_b32_e32 v35, v0
	v_mov_b32_e32 v36, v0
	v_mov_b32_e32 v37, v0
	v_mov_b32_e32 v38, v0
	v_mov_b32_e32 v39, v0
	v_mov_b32_e32 v48, v0
	v_mov_b32_e32 v49, v0
	v_mov_b32_e32 v50, v0
	v_mov_b32_e32 v51, v0
	v_mov_b32_e32 v52, v0
	v_mov_b32_e32 v53, v0
	v_mov_b32_e32 v54, v0
	v_mov_b32_e32 v55, v0
	v_mov_b32_e32 v8, v0
	v_mov_b32_e32 v9, v0
	v_mov_b32_e32 v10, v0
	v_mov_b32_e32 v11, v0
	v_mov_b32_e32 v12, v0
	v_mov_b32_e32 v13, v0
	v_mov_b32_e32 v14, v0
	v_mov_b32_e32 v15, v0
	v_mov_b32_e32 v24, v0
	v_mov_b32_e32 v25, v0
	v_mov_b32_e32 v26, v0
	v_mov_b32_e32 v27, v0
	v_mov_b32_e32 v28, v0
	v_mov_b32_e32 v29, v0
	v_mov_b32_e32 v30, v0
	v_mov_b32_e32 v31, v0
	v_mov_b32_e32 v40, v0
	v_mov_b32_e32 v41, v0
	v_mov_b32_e32 v42, v0
	v_mov_b32_e32 v43, v0
	v_mov_b32_e32 v44, v0
	v_mov_b32_e32 v45, v0
	v_mov_b32_e32 v46, v0
	v_mov_b32_e32 v47, v0
	v_mov_b32_e32 v56, v0
	v_mov_b32_e32 v57, v0
	v_mov_b32_e32 v58, v0
	v_mov_b32_e32 v59, v0
	v_mov_b32_e32 v60, v0
	v_mov_b32_e32 v61, v0
	v_mov_b32_e32 v62, v0
	v_mov_b32_e32 v63, v0
	v_mov_b32_e32 v64, v0
	v_mov_b32_e32 v65, v0
	v_mov_b32_e32 v66, v0
	v_mov_b32_e32 v67, v0
	v_mov_b32_e32 v68, v0
	v_mov_b32_e32 v69, v0
	v_mov_b32_e32 v70, v0
	v_mov_b32_e32 v71, v0
	v_mov_b32_e32 v80, v0
	v_mov_b32_e32 v81, v0
	v_mov_b32_e32 v82, v0
	v_mov_b32_e32 v83, v0
	v_mov_b32_e32 v84, v0
	v_mov_b32_e32 v85, v0
	v_mov_b32_e32 v86, v0
	v_mov_b32_e32 v87, v0
	v_mov_b32_e32 v96, v0
	v_mov_b32_e32 v97, v0
	v_mov_b32_e32 v98, v0
	v_mov_b32_e32 v99, v0
	v_mov_b32_e32 v100, v0
	v_mov_b32_e32 v101, v0
	v_mov_b32_e32 v102, v0
	v_mov_b32_e32 v103, v0
	v_mov_b32_e32 v112, v0
	v_mov_b32_e32 v113, v0
	v_mov_b32_e32 v114, v0
	v_mov_b32_e32 v115, v0
	v_mov_b32_e32 v116, v0
	v_mov_b32_e32 v117, v0
	v_mov_b32_e32 v118, v0
	v_mov_b32_e32 v119, v0
	v_mov_b32_e32 v72, v0
	v_mov_b32_e32 v73, v0
	v_mov_b32_e32 v74, v0
	v_mov_b32_e32 v75, v0
	v_mov_b32_e32 v76, v0
	v_mov_b32_e32 v77, v0
	v_mov_b32_e32 v78, v0
	v_mov_b32_e32 v79, v0
	v_mov_b32_e32 v88, v0
	v_mov_b32_e32 v89, v0
	v_mov_b32_e32 v90, v0
	v_mov_b32_e32 v91, v0
	v_mov_b32_e32 v92, v0
	v_mov_b32_e32 v93, v0
	v_mov_b32_e32 v94, v0
	v_mov_b32_e32 v95, v0
	v_mov_b32_e32 v104, v0
	v_mov_b32_e32 v105, v0
	v_mov_b32_e32 v106, v0
	v_mov_b32_e32 v107, v0
	v_mov_b32_e32 v108, v0
	v_mov_b32_e32 v109, v0
	v_mov_b32_e32 v110, v0
	v_mov_b32_e32 v111, v0
	v_mov_b32_e32 v120, v0
	v_mov_b32_e32 v121, v0
	v_mov_b32_e32 v122, v0
	v_mov_b32_e32 v123, v0
	v_mov_b32_e32 v124, v0
	v_mov_b32_e32 v125, v0
	v_mov_b32_e32 v126, v0
	v_mov_b32_e32 v127, v0

.LBB0_672:
	s_ashr_i32 s25, s24, 31
	s_lshl_b64 s[26:27], s[24:25], 20
	s_add_u32 s26, s38, s26
	s_addc_u32 s27, s39, s27
	s_and_b64 s[28:29], s[6:7], exec
	s_cselect_b32 s25, s27, s31
	s_cselect_b32 s65, s26, s30
	s_ashr_i32 s23, s22, 31
	s_lshl_b64 s[28:29], s[22:23], 20
	s_add_u32 s28, s40, s28
	s_addc_u32 s29, s41, s29
	s_and_b64 s[36:37], s[6:7], exec
	s_cselect_b32 s23, s29, s35
	s_cselect_b32 s66, s28, s34
	s_add_u32 s30, s30, 0x80080
	s_addc_u32 s31, s31, 0
	s_add_u32 s67, s34, 0x100
	v_mov_b32_e32 v8, 0
	s_addc_u32 s68, s35, 0
	s_mov_b32 s69, -2
	v_mov_b32_e32 v9, v8
	v_mov_b32_e32 v10, v8
	v_mov_b32_e32 v11, v8
	v_mov_b32_e32 v12, v8
	v_mov_b32_e32 v13, v8
	v_mov_b32_e32 v14, v8
	v_mov_b32_e32 v15, v8
	v_mov_b32_e32 v24, v8
	v_mov_b32_e32 v25, v8
	v_mov_b32_e32 v26, v8
	v_mov_b32_e32 v27, v8
	v_mov_b32_e32 v28, v8
	v_mov_b32_e32 v29, v8
	v_mov_b32_e32 v30, v8
	v_mov_b32_e32 v31, v8
	v_mov_b32_e32 v40, v8
	v_mov_b32_e32 v41, v8
	v_mov_b32_e32 v42, v8
	v_mov_b32_e32 v43, v8
	v_mov_b32_e32 v44, v8
	v_mov_b32_e32 v45, v8
	v_mov_b32_e32 v46, v8
	v_mov_b32_e32 v47, v8
	v_mov_b32_e32 v56, v8
	v_mov_b32_e32 v57, v8
	v_mov_b32_e32 v58, v8
	v_mov_b32_e32 v59, v8
	v_mov_b32_e32 v60, v8
	v_mov_b32_e32 v61, v8
	v_mov_b32_e32 v62, v8
	v_mov_b32_e32 v63, v8
	v_mov_b32_e32 v0, v8
	v_mov_b32_e32 v1, v8
	v_mov_b32_e32 v2, v8
	v_mov_b32_e32 v3, v8
	v_mov_b32_e32 v4, v8
	v_mov_b32_e32 v5, v8
	v_mov_b32_e32 v6, v8
	v_mov_b32_e32 v7, v8
	v_mov_b32_e32 v16, v8
	v_mov_b32_e32 v17, v8
	v_mov_b32_e32 v18, v8
	v_mov_b32_e32 v19, v8
	v_mov_b32_e32 v20, v8
	v_mov_b32_e32 v21, v8
	v_mov_b32_e32 v22, v8
	v_mov_b32_e32 v23, v8
	v_mov_b32_e32 v32, v8
	v_mov_b32_e32 v33, v8
	v_mov_b32_e32 v34, v8
	v_mov_b32_e32 v35, v8
	v_mov_b32_e32 v36, v8
	v_mov_b32_e32 v37, v8
	v_mov_b32_e32 v38, v8
	v_mov_b32_e32 v39, v8
	v_mov_b32_e32 v48, v8
	v_mov_b32_e32 v49, v8
	v_mov_b32_e32 v50, v8
	v_mov_b32_e32 v51, v8
	v_mov_b32_e32 v52, v8
	v_mov_b32_e32 v53, v8
	v_mov_b32_e32 v54, v8
	v_mov_b32_e32 v55, v8
	v_mov_b32_e32 v72, v8
	v_mov_b32_e32 v73, v8
	v_mov_b32_e32 v74, v8
	v_mov_b32_e32 v75, v8
	v_mov_b32_e32 v76, v8
	v_mov_b32_e32 v77, v8
	v_mov_b32_e32 v78, v8
	v_mov_b32_e32 v79, v8
	v_mov_b32_e32 v88, v8
	v_mov_b32_e32 v89, v8
	v_mov_b32_e32 v90, v8
	v_mov_b32_e32 v91, v8
	v_mov_b32_e32 v92, v8
	v_mov_b32_e32 v93, v8
	v_mov_b32_e32 v94, v8
	v_mov_b32_e32 v95, v8
	v_mov_b32_e32 v104, v8
	v_mov_b32_e32 v105, v8
	v_mov_b32_e32 v106, v8
	v_mov_b32_e32 v107, v8
	v_mov_b32_e32 v108, v8
	v_mov_b32_e32 v109, v8
	v_mov_b32_e32 v110, v8
	v_mov_b32_e32 v111, v8
	v_mov_b32_e32 v120, v8
	v_mov_b32_e32 v121, v8
	v_mov_b32_e32 v122, v8
	v_mov_b32_e32 v123, v8
	v_mov_b32_e32 v124, v8
	v_mov_b32_e32 v125, v8
	v_mov_b32_e32 v126, v8
	v_mov_b32_e32 v127, v8
	v_mov_b32_e32 v64, v8
	v_mov_b32_e32 v65, v8
	v_mov_b32_e32 v66, v8
	v_mov_b32_e32 v67, v8
	v_mov_b32_e32 v68, v8
	v_mov_b32_e32 v69, v8
	v_mov_b32_e32 v70, v8
	v_mov_b32_e32 v71, v8
	v_mov_b32_e32 v80, v8
	v_mov_b32_e32 v81, v8
	v_mov_b32_e32 v82, v8
	v_mov_b32_e32 v83, v8
	v_mov_b32_e32 v84, v8
	v_mov_b32_e32 v85, v8
	v_mov_b32_e32 v86, v8
	v_mov_b32_e32 v87, v8
	v_mov_b32_e32 v96, v8
	v_mov_b32_e32 v97, v8
	v_mov_b32_e32 v98, v8
	v_mov_b32_e32 v99, v8
	v_mov_b32_e32 v100, v8
	v_mov_b32_e32 v101, v8
	v_mov_b32_e32 v102, v8
	v_mov_b32_e32 v103, v8
	v_mov_b32_e32 v112, v8
	v_mov_b32_e32 v113, v8
	v_mov_b32_e32 v114, v8
	v_mov_b32_e32 v115, v8
	v_mov_b32_e32 v116, v8
	v_mov_b32_e32 v117, v8
	v_mov_b32_e32 v118, v8
	v_mov_b32_e32 v119, v8

.LBB0_1186:
	s_add_u32 s66, s30, 0x100
	v_mov_b32_e32 v0, 0
	s_addc_u32 s67, s31, 0
	s_mov_b32 s68, -2
	s_waitcnt lgkmcnt(0)
	v_mov_b32_e32 v1, v0
	v_mov_b32_e32 v2, v0
	v_mov_b32_e32 v3, v0
	v_mov_b32_e32 v4, v0
	v_mov_b32_e32 v5, v0
	v_mov_b32_e32 v6, v0
	v_mov_b32_e32 v7, v0
	v_mov_b32_e32 v16, v0
	v_mov_b32_e32 v17, v0
	v_mov_b32_e32 v18, v0
	v_mov_b32_e32 v19, v0
	v_mov_b32_e32 v20, v0
	v_mov_b32_e32 v21, v0
	v_mov_b32_e32 v22, v0
	v_mov_b32_e32 v23, v0
	v_mov_b32_e32 v32, v0
	v_mov_b32_e32 v33, v0
	v_mov_b32_e32 v34, v0
	v_mov_b32_e32 v35, v0
	v_mov_b32_e32 v36, v0
	v_mov_b32_e32 v37, v0
	v_mov_b32_e32 v38, v0
	v_mov_b32_e32 v39, v0
	v_mov_b32_e32 v48, v0
	v_mov_b32_e32 v49, v0
	v_mov_b32_e32 v50, v0
	v_mov_b32_e32 v51, v0
	v_mov_b32_e32 v52, v0
	v_mov_b32_e32 v53, v0
	v_mov_b32_e32 v54, v0
	v_mov_b32_e32 v55, v0
	v_mov_b32_e32 v8, v0
	v_mov_b32_e32 v9, v0
	v_mov_b32_e32 v10, v0
	v_mov_b32_e32 v11, v0
	v_mov_b32_e32 v12, v0
	v_mov_b32_e32 v13, v0
	v_mov_b32_e32 v14, v0
	v_mov_b32_e32 v15, v0
	v_mov_b32_e32 v24, v0
	v_mov_b32_e32 v25, v0
	v_mov_b32_e32 v26, v0
	v_mov_b32_e32 v27, v0
	v_mov_b32_e32 v28, v0
	v_mov_b32_e32 v29, v0
	v_mov_b32_e32 v30, v0
	v_mov_b32_e32 v31, v0
	v_mov_b32_e32 v40, v0
	v_mov_b32_e32 v41, v0
	v_mov_b32_e32 v42, v0
	v_mov_b32_e32 v43, v0
	v_mov_b32_e32 v44, v0
	v_mov_b32_e32 v45, v0
	v_mov_b32_e32 v46, v0
	v_mov_b32_e32 v47, v0
	v_mov_b32_e32 v56, v0
	v_mov_b32_e32 v57, v0
	v_mov_b32_e32 v58, v0
	v_mov_b32_e32 v59, v0
	v_mov_b32_e32 v60, v0
	v_mov_b32_e32 v61, v0
	v_mov_b32_e32 v62, v0
	v_mov_b32_e32 v63, v0
	v_mov_b32_e32 v64, v0
	v_mov_b32_e32 v65, v0
	v_mov_b32_e32 v66, v0
	v_mov_b32_e32 v67, v0
	v_mov_b32_e32 v68, v0
	v_mov_b32_e32 v69, v0
	v_mov_b32_e32 v70, v0
	v_mov_b32_e32 v71, v0
	v_mov_b32_e32 v80, v0
	v_mov_b32_e32 v81, v0
	v_mov_b32_e32 v82, v0
	v_mov_b32_e32 v83, v0
	v_mov_b32_e32 v84, v0
	v_mov_b32_e32 v85, v0
	v_mov_b32_e32 v86, v0
	v_mov_b32_e32 v87, v0
	v_mov_b32_e32 v96, v0
	v_mov_b32_e32 v97, v0
	v_mov_b32_e32 v98, v0
	v_mov_b32_e32 v99, v0
	v_mov_b32_e32 v100, v0
	v_mov_b32_e32 v101, v0
	v_mov_b32_e32 v102, v0
	v_mov_b32_e32 v103, v0
	v_mov_b32_e32 v112, v0
	v_mov_b32_e32 v113, v0
	v_mov_b32_e32 v114, v0
	v_mov_b32_e32 v115, v0
	v_mov_b32_e32 v116, v0
	v_mov_b32_e32 v117, v0
	v_mov_b32_e32 v118, v0
	v_mov_b32_e32 v119, v0
	v_mov_b32_e32 v72, v0
	v_mov_b32_e32 v73, v0
	v_mov_b32_e32 v74, v0
	v_mov_b32_e32 v75, v0
	v_mov_b32_e32 v76, v0
	v_mov_b32_e32 v77, v0
	v_mov_b32_e32 v78, v0
	v_mov_b32_e32 v79, v0
	v_mov_b32_e32 v88, v0
	v_mov_b32_e32 v89, v0
	v_mov_b32_e32 v90, v0
	v_mov_b32_e32 v91, v0
	v_mov_b32_e32 v92, v0
	v_mov_b32_e32 v93, v0
	v_mov_b32_e32 v94, v0
	v_mov_b32_e32 v95, v0
	v_mov_b32_e32 v104, v0
	v_mov_b32_e32 v105, v0
	v_mov_b32_e32 v106, v0
	v_mov_b32_e32 v107, v0
	v_mov_b32_e32 v108, v0
	v_mov_b32_e32 v109, v0
	v_mov_b32_e32 v110, v0
	v_mov_b32_e32 v111, v0
	v_mov_b32_e32 v120, v0
	v_mov_b32_e32 v121, v0
	v_mov_b32_e32 v122, v0
	v_mov_b32_e32 v123, v0
	v_mov_b32_e32 v124, v0
	v_mov_b32_e32 v125, v0
	v_mov_b32_e32 v126, v0
	v_mov_b32_e32 v127, v0

.LBB0_1270:
	s_ashr_i32 s25, s24, 31
	s_lshl_b64 s[26:27], s[24:25], 20
	s_add_u32 s26, s38, s26
	s_addc_u32 s27, s39, s27
	s_and_b64 s[28:29], s[6:7], exec
	s_cselect_b32 s25, s27, s31
	s_cselect_b32 s63, s26, s30
	s_ashr_i32 s23, s22, 31
	s_lshl_b64 s[28:29], s[22:23], 20
	s_add_u32 s28, s40, s28
	s_addc_u32 s29, s41, s29
	s_and_b64 s[36:37], s[6:7], exec
	s_cselect_b32 s23, s29, s35
	s_cselect_b32 s64, s28, s34
	s_add_u32 s30, s30, 0x80080
	s_addc_u32 s31, s31, 0
	s_add_u32 s65, s34, 0x100
	v_mov_b32_e32 v0, 0
	s_addc_u32 s66, s35, 0
	s_mov_b32 s67, -2
	v_mov_b32_e32 v1, v0
	v_mov_b32_e32 v2, v0
	v_mov_b32_e32 v3, v0
	v_mov_b32_e32 v4, v0
	v_mov_b32_e32 v5, v0
	v_mov_b32_e32 v6, v0
	v_mov_b32_e32 v7, v0
	v_mov_b32_e32 v16, v0
	v_mov_b32_e32 v17, v0
	v_mov_b32_e32 v18, v0
	v_mov_b32_e32 v19, v0
	v_mov_b32_e32 v20, v0
	v_mov_b32_e32 v21, v0
	v_mov_b32_e32 v22, v0
	v_mov_b32_e32 v23, v0
	v_mov_b32_e32 v32, v0
	v_mov_b32_e32 v33, v0
	v_mov_b32_e32 v34, v0
	v_mov_b32_e32 v35, v0
	v_mov_b32_e32 v36, v0
	v_mov_b32_e32 v37, v0
	v_mov_b32_e32 v38, v0
	v_mov_b32_e32 v39, v0
	v_mov_b32_e32 v48, v0
	v_mov_b32_e32 v49, v0
	v_mov_b32_e32 v50, v0
	v_mov_b32_e32 v51, v0
	v_mov_b32_e32 v52, v0
	v_mov_b32_e32 v53, v0
	v_mov_b32_e32 v54, v0
	v_mov_b32_e32 v55, v0
	v_mov_b32_e32 v8, v0
	v_mov_b32_e32 v9, v0
	v_mov_b32_e32 v10, v0
	v_mov_b32_e32 v11, v0
	v_mov_b32_e32 v12, v0
	v_mov_b32_e32 v13, v0
	v_mov_b32_e32 v14, v0
	v_mov_b32_e32 v15, v0
	v_mov_b32_e32 v24, v0
	v_mov_b32_e32 v25, v0
	v_mov_b32_e32 v26, v0
	v_mov_b32_e32 v27, v0
	v_mov_b32_e32 v28, v0
	v_mov_b32_e32 v29, v0
	v_mov_b32_e32 v30, v0
	v_mov_b32_e32 v31, v0
	v_mov_b32_e32 v40, v0
	v_mov_b32_e32 v41, v0
	v_mov_b32_e32 v42, v0
	v_mov_b32_e32 v43, v0
	v_mov_b32_e32 v44, v0
	v_mov_b32_e32 v45, v0
	v_mov_b32_e32 v46, v0
	v_mov_b32_e32 v47, v0
	v_mov_b32_e32 v56, v0
	v_mov_b32_e32 v57, v0
	v_mov_b32_e32 v58, v0
	v_mov_b32_e32 v59, v0
	v_mov_b32_e32 v60, v0
	v_mov_b32_e32 v61, v0
	v_mov_b32_e32 v62, v0
	v_mov_b32_e32 v63, v0
	v_mov_b32_e32 v64, v0
	v_mov_b32_e32 v65, v0
	v_mov_b32_e32 v66, v0
	v_mov_b32_e32 v67, v0
	v_mov_b32_e32 v68, v0
	v_mov_b32_e32 v69, v0
	v_mov_b32_e32 v70, v0
	v_mov_b32_e32 v71, v0
	v_mov_b32_e32 v80, v0
	v_mov_b32_e32 v81, v0
	v_mov_b32_e32 v82, v0
	v_mov_b32_e32 v83, v0
	v_mov_b32_e32 v84, v0
	v_mov_b32_e32 v85, v0
	v_mov_b32_e32 v86, v0
	v_mov_b32_e32 v87, v0
	v_mov_b32_e32 v96, v0
	v_mov_b32_e32 v97, v0
	v_mov_b32_e32 v98, v0
	v_mov_b32_e32 v99, v0
	v_mov_b32_e32 v100, v0
	v_mov_b32_e32 v101, v0
	v_mov_b32_e32 v102, v0
	v_mov_b32_e32 v103, v0
	v_mov_b32_e32 v112, v0
	v_mov_b32_e32 v113, v0
	v_mov_b32_e32 v114, v0
	v_mov_b32_e32 v115, v0
	v_mov_b32_e32 v116, v0
	v_mov_b32_e32 v117, v0
	v_mov_b32_e32 v118, v0
	v_mov_b32_e32 v119, v0
	v_mov_b32_e32 v72, v0
	v_mov_b32_e32 v73, v0
	v_mov_b32_e32 v74, v0
	v_mov_b32_e32 v75, v0
	v_mov_b32_e32 v76, v0
	v_mov_b32_e32 v77, v0
	v_mov_b32_e32 v78, v0
	v_mov_b32_e32 v79, v0
	v_mov_b32_e32 v88, v0
	v_mov_b32_e32 v89, v0
	v_mov_b32_e32 v90, v0
	v_mov_b32_e32 v91, v0
	v_mov_b32_e32 v92, v0
	v_mov_b32_e32 v93, v0
	v_mov_b32_e32 v94, v0
	v_mov_b32_e32 v95, v0
	v_mov_b32_e32 v104, v0
	v_mov_b32_e32 v105, v0
	v_mov_b32_e32 v106, v0
	v_mov_b32_e32 v107, v0
	v_mov_b32_e32 v108, v0
	v_mov_b32_e32 v109, v0
	v_mov_b32_e32 v110, v0
	v_mov_b32_e32 v111, v0
	v_mov_b32_e32 v120, v0
	v_mov_b32_e32 v121, v0
	v_mov_b32_e32 v122, v0
	v_mov_b32_e32 v123, v0
	v_mov_b32_e32 v124, v0
	v_mov_b32_e32 v125, v0
	v_mov_b32_e32 v126, v0
	v_mov_b32_e32 v127, v0
